# context-row norm_rows (one row per wave, on the critical path of 32 workgroups before the layer-end grid barrier) rewritten by hand: all 32 loads together, one wait
# speedup vs baseline: 1.0053x; 1.0038x over previous
; __device__ __forceinline__ void norm_rows(const float* X, const float* nw, const float* md, u16* H, int row0, int nrows, int wave, int lane) {
;     for (int row = row0 + wave; row < row0 + nrows; row += 8) {
;         const float4* xr = (const float4*)(X + (size_t)row * DM) + lane; float4 v[8]; float ss = 0.f;
; #pragma unroll
;         for (int j = 0; j < 8; ++j) { v[j] = xr[64 * j]; ss += v[j].x * v[j].x + v[j].y * v[j].y + v[j].z * v[j].z + v[j].w * v[j].w; }
;         const float r = rsqrtf(wave_sum(ss) * (1.f / DM) + EPS);
;         uint2* hp = (uint2*)(H + (size_t)row * DM) + lane;
; #pragma unroll
;         for (int j = 0; j < 8; ++j) { const int col = 4 * (lane + 64 * j); const float4 w4 = *(const float4*)(nw + col), sc = *(const float4*)(md + 2048 + col), sh = *(const float4*)(md + col);
.LBB0_1309:
	s_or_b64 exec, exec, s[40:41]
	v_mov_b32_e32 v1, v170
	s_waitcnt lgkmcnt(0)
	s_barrier
	s_nop 0
	v_ashrrev_i32_e32 v0, 6, v1
	v_cmp_gt_i32_e32 vcc, 8, v0
	s_and_saveexec_b64 s[38:39], vcc
	v_readlane_b32 s16, v254, 16
	v_readlane_b32 s20, v254, 20
	v_readlane_b32 s21, v254, 21
	v_readlane_b32 s22, v254, 22
	v_readlane_b32 s23, v254, 23
	v_readlane_b32 s17, v254, 17
	v_readlane_b32 s18, v254, 18
	v_readlane_b32 s19, v254, 19
	s_cbranch_execz .LBB0_1312
	v_cmp_lt_i32_e32 vcc, v178, v172
	s_add_u32 s6, s34, 0x6000
	s_addc_u32 s7, s35, 0
	v_cndmask_b32_e32 v3, v171, v178, vcc
	v_cmp_lt_i32_e32 vcc, v177, v172
	v_lshlrev_b32_e32 v71, 2, v3
	v_and_b32_e32 v1, 63, v1
	v_cndmask_b32_e32 v3, v171, v177, vcc
	v_cmp_lt_i32_e32 vcc, v176, v172
	v_lshlrev_b32_e32 v96, 2, v3
	s_add_u32 s12, s34, 0x8000
	v_cndmask_b32_e32 v3, v171, v176, vcc
	v_lshlrev_b32_e32 v97, 2, v3
	v_xor_b32_e32 v3, 8, v171
	v_cmp_lt_i32_e32 vcc, v3, v172
	v_lshlrev_b32_e32 v164, 4, v1
	s_addc_u32 s13, s35, 0
	v_cndmask_b32_e32 v3, v171, v3, vcc
	v_lshlrev_b32_e32 v98, 2, v3
	v_xor_b32_e32 v3, 16, v171
	v_or_b32_e32 v4, 0x400, v164
	v_mov_b32_e32 v5, v165
	v_cmp_lt_i32_e32 vcc, v3, v172
	v_lshl_add_u64 v[30:31], s[12:13], 0, v[4:5]
	v_lshl_add_u64 v[32:33], s[6:7], 0, v[4:5]
	v_or_b32_e32 v4, 0x800, v164
	v_cndmask_b32_e32 v3, v171, v3, vcc
	v_lshl_add_u64 v[34:35], s[12:13], 0, v[4:5]
	v_lshl_add_u64 v[36:37], s[6:7], 0, v[4:5]
	v_or_b32_e32 v4, 0xc00, v164
	v_lshlrev_b32_e32 v99, 2, v3
	v_xor_b32_e32 v3, 32, v171
	v_lshl_add_u64 v[38:39], s[12:13], 0, v[4:5]
	v_lshl_add_u64 v[40:41], s[6:7], 0, v[4:5]
	v_or_b32_e32 v4, 0x1000, v164
	v_cmp_lt_i32_e32 vcc, v3, v172
	v_lshl_add_u64 v[42:43], s[0:1], 0, v[4:5]
	v_lshl_add_u64 v[44:45], s[12:13], 0, v[4:5]
	v_lshl_add_u64 v[46:47], s[6:7], 0, v[4:5]
	v_or_b32_e32 v4, 0x1400, v164
	v_add_u32_e32 v2, s11, v0
	v_cndmask_b32_e32 v3, v171, v3, vcc
	v_lshl_add_u64 v[48:49], s[0:1], 0, v[4:5]
	v_lshl_add_u64 v[50:51], s[12:13], 0, v[4:5]
	v_lshl_add_u64 v[52:53], s[6:7], 0, v[4:5]
	v_or_b32_e32 v4, 0x1800, v164
	v_lshlrev_b32_e32 v100, 2, v3
	v_lshl_add_u64 v[54:55], s[0:1], 0, v[4:5]
	v_lshl_add_u64 v[56:57], s[12:13], 0, v[4:5]
	v_lshl_add_u64 v[58:59], s[6:7], 0, v[4:5]
	v_or_b32_e32 v4, 0x1c00, v164
	v_ashrrev_i32_e32 v3, 31, v2
	v_lshl_add_u64 v[24:25], s[0:1], 0, v[164:165]
	v_lshl_add_u64 v[60:61], s[0:1], 0, v[4:5]
	v_readlane_b32 s0, v254, 28
	v_lshlrev_b64 v[66:67], 13, v[2:3]
	v_lshlrev_b64 v[68:69], 12, v[2:3]
	s_mov_b64 s[54:55], s[22:23]
	v_lshl_add_u64 v[26:27], s[12:13], 0, v[164:165]
	v_lshl_add_u64 v[28:29], s[6:7], 0, v[164:165]
	v_lshl_add_u64 v[62:63], s[12:13], 0, v[4:5]
	v_lshl_add_u64 v[64:65], s[6:7], 0, v[4:5]
	v_add_u32_e32 v101, s0, v0
	v_or_b32_e32 v66, v66, v164
	v_lshl_or_b32 v68, v1, 3, v68
	s_mov_b64 s[0:1], 0
	s_mov_b64 s[52:53], s[20:21]
	global_load_dwordx4 v[182:185], v[24:25], off
	global_load_dwordx4 v[186:189], v[24:25], off offset:1024
	global_load_dwordx4 v[190:193], v[24:25], off offset:2048
	global_load_dwordx4 v[194:197], v[24:25], off offset:3072
	global_load_dwordx4 v[198:201], v[42:43], off
	global_load_dwordx4 v[202:205], v[48:49], off
	global_load_dwordx4 v[206:209], v[54:55], off
	global_load_dwordx4 v[210:213], v[60:61], off
	global_load_dwordx4 v[214:217], v[26:27], off
	global_load_dwordx4 v[218:221], v[30:31], off
	global_load_dwordx4 v[222:225], v[34:35], off
	global_load_dwordx4 v[226:229], v[38:39], off
	global_load_dwordx4 v[230:233], v[44:45], off
	global_load_dwordx4 v[234:237], v[50:51], off
	global_load_dwordx4 v[238:241], v[56:57], off
	global_load_dwordx4 v[242:245], v[62:63], off
	global_load_dwordx4 v[0:3], v[28:29], off
	global_load_dwordx4 v[4:7], v[32:33], off
	global_load_dwordx4 v[8:11], v[36:37], off
	global_load_dwordx4 v[12:15], v[40:41], off
	global_load_dwordx4 v[16:19], v[46:47], off
	global_load_dwordx4 v[20:23], v[52:53], off
	global_load_dwordx4 v[136:139], v[58:59], off
	global_load_dwordx4 v[140:143], v[64:65], off
	s_mov_b32 s101, 0x7060302
	v_lshl_add_u64 v[74:75], s[54:55], 0, v[66:67]
	v_add_co_u32_e32 v76, vcc, s64, v74
	s_nop 1
	v_addc_co_u32_e32 v77, vcc, 0, v75, vcc
	v_add_co_u32_e32 v74, vcc, 0xa000000, v74
	s_nop 1
	v_addc_co_u32_e32 v75, vcc, 0, v75, vcc
	global_load_dwordx4 v[104:107], v[74:75], off
	global_load_dwordx4 v[108:111], v[74:75], off offset:1024
	global_load_dwordx4 v[112:115], v[74:75], off offset:2048
	global_load_dwordx4 v[116:119], v[74:75], off offset:3072
	global_load_dwordx4 v[120:123], v[76:77], off
	global_load_dwordx4 v[124:127], v[76:77], off offset:1024
	global_load_dwordx4 v[128:131], v[76:77], off offset:2048
	global_load_dwordx4 v[132:135], v[76:77], off offset:3072
	v_lshl_add_u64 v[78:79], s[54:55], 0, v[68:69]
	v_add_co_u32_e32 v78, vcc, s66, v78
	s_nop 1
	v_addc_co_u32_e32 v79, vcc, 0, v79, vcc
	s_waitcnt vmcnt(0)
; __device__ __forceinline__ unsigned pk2(float lo, float hi) { return f2bf(lo) | (f2bf(hi) << 16); }
; __device__ __forceinline__ void norm_rows(const float* X, const float* nw, const float* md, u16* H, int row0, int nrows, int wave, int lane) {
;     ...
;         for (int j = 0; j < 8; ++j) { v[j] = xr[64 * j]; ss += v[j].x * v[j].x + v[j].y * v[j].y + v[j].z * v[j].z + v[j].w * v[j].w; }
;         const float r = rsqrtf(wave_sum(ss) * (1.f / DM) + EPS);
;         uint2* hp = (uint2*)(H + (size_t)row * DM) + lane;
; #pragma unroll
;         for (int j = 0; j < 8; ++j) { const int col = 4 * (lane + 64 * j); const float4 w4 = *(const float4*)(nw + col), sc = *(const float4*)(md + 2048 + col), sh = *(const float4*)(md + col);
;             uint2 o; o.x = pk2(v[j].x * r * w4.x * (1.f + sc.x) + sh.x, v[j].y * r * w4.y * (1.f + sc.y) + sh.y);
	v_add_f32_e32 v214, 1.0, v214
	v_add_f32_e32 v215, 1.0, v215
	v_add_f32_e32 v216, 1.0, v216
	v_add_f32_e32 v217, 1.0, v217
	v_add_f32_e32 v218, 1.0, v218
	v_add_f32_e32 v219, 1.0, v219
	v_add_f32_e32 v220, 1.0, v220
	v_add_f32_e32 v221, 1.0, v221
	v_add_f32_e32 v222, 1.0, v222
	v_add_f32_e32 v223, 1.0, v223
	v_add_f32_e32 v224, 1.0, v224
	v_add_f32_e32 v225, 1.0, v225
	v_add_f32_e32 v226, 1.0, v226
	v_add_f32_e32 v227, 1.0, v227
	v_add_f32_e32 v228, 1.0, v228
	v_add_f32_e32 v229, 1.0, v229
	v_add_f32_e32 v230, 1.0, v230
	v_add_f32_e32 v231, 1.0, v231
	v_add_f32_e32 v232, 1.0, v232
	v_add_f32_e32 v233, 1.0, v233
	v_add_f32_e32 v234, 1.0, v234
	v_add_f32_e32 v235, 1.0, v235
	v_add_f32_e32 v236, 1.0, v236
	v_add_f32_e32 v237, 1.0, v237
	v_add_f32_e32 v238, 1.0, v238
	v_add_f32_e32 v239, 1.0, v239
	v_add_f32_e32 v240, 1.0, v240
	v_add_f32_e32 v241, 1.0, v241
	v_add_f32_e32 v242, 1.0, v242
	v_add_f32_e32 v243, 1.0, v243
	v_add_f32_e32 v244, 1.0, v244
	v_add_f32_e32 v245, 1.0, v245
	v_mul_f32_e32 v81, v105, v105
	v_fmac_f32_e32 v81, v104, v104
	v_fmac_f32_e32 v81, v106, v106
	v_fmac_f32_e32 v81, v107, v107
	v_mul_f32_e32 v80, v109, v109
	v_fmac_f32_e32 v80, v108, v108
	v_fmac_f32_e32 v80, v110, v110
	v_fmac_f32_e32 v80, v111, v111
	v_add_f32_e32 v81, v81, v80
	v_mul_f32_e32 v80, v113, v113
	v_fmac_f32_e32 v80, v112, v112
	v_fmac_f32_e32 v80, v114, v114
	v_fmac_f32_e32 v80, v115, v115
	v_add_f32_e32 v81, v81, v80
	v_mul_f32_e32 v80, v117, v117
	v_fmac_f32_e32 v80, v116, v116
	v_fmac_f32_e32 v80, v118, v118
	v_fmac_f32_e32 v80, v119, v119
	v_add_f32_e32 v81, v81, v80
	v_mul_f32_e32 v80, v121, v121
	v_fmac_f32_e32 v80, v120, v120
	v_fmac_f32_e32 v80, v122, v122
	v_fmac_f32_e32 v80, v123, v123
	v_add_f32_e32 v81, v81, v80
	v_mul_f32_e32 v80, v125, v125
	v_fmac_f32_e32 v80, v124, v124
	v_fmac_f32_e32 v80, v126, v126
	v_fmac_f32_e32 v80, v127, v127
	v_add_f32_e32 v81, v81, v80
	v_mul_f32_e32 v80, v129, v129
	v_fmac_f32_e32 v80, v128, v128
	v_fmac_f32_e32 v80, v130, v130
	v_fmac_f32_e32 v80, v131, v131
	v_add_f32_e32 v81, v81, v80
	v_mul_f32_e32 v80, v133, v133
	v_fmac_f32_e32 v80, v132, v132
	v_fmac_f32_e32 v80, v134, v134
	v_fmac_f32_e32 v80, v135, v135
	v_add_f32_e32 v81, v81, v80
	ds_bpermute_b32 v80, v71, v81
	s_waitcnt lgkmcnt(0)
	v_add_f32_e32 v81, v81, v80
	ds_bpermute_b32 v80, v96, v81
	s_waitcnt lgkmcnt(0)
	v_add_f32_e32 v81, v81, v80
	ds_bpermute_b32 v80, v97, v81
	s_waitcnt lgkmcnt(0)
	v_add_f32_e32 v81, v81, v80
	ds_bpermute_b32 v80, v98, v81
	s_waitcnt lgkmcnt(0)
	v_add_f32_e32 v81, v81, v80
	ds_bpermute_b32 v80, v99, v81
	s_waitcnt lgkmcnt(0)
	v_add_f32_e32 v81, v81, v80
	ds_bpermute_b32 v80, v100, v81
	s_waitcnt lgkmcnt(0)
; __device__ __forceinline__ unsigned pk2(float lo, float hi) { return f2bf(lo) | (f2bf(hi) << 16); }
; __device__ __forceinline__ void norm_rows(const float* X, const float* nw, const float* md, u16* H, int row0, int nrows, int wave, int lane) {
;     ...
;         const float r = rsqrtf(wave_sum(ss) * (1.f / DM) + EPS);
;         uint2* hp = (uint2*)(H + (size_t)row * DM) + lane;
; #pragma unroll
;         for (int j = 0; j < 8; ++j) { const int col = 4 * (lane + 64 * j); const float4 w4 = *(const float4*)(nw + col), sc = *(const float4*)(md + 2048 + col), sh = *(const float4*)(md + col);
;             uint2 o; o.x = pk2(v[j].x * r * w4.x * (1.f + sc.x) + sh.x, v[j].y * r * w4.y * (1.f + sc.y) + sh.y);
;             o.y = pk2(v[j].z * r * w4.z * (1.f + sc.z) + sh.z, v[j].w * r * w4.w * (1.f + sc.w) + sh.w); hp[64 * j] = o; } }
	v_add_f32_e32 v81, v81, v80
	v_fmamk_f32 v81, v81, 0x3a000000, v179
	v_cmp_gt_f32_e32 vcc, s91, v81
	v_mul_f32_e32 v80, 0x4b800000, v81
	s_nop 0
	v_cndmask_b32_e32 v81, v81, v80, vcc
	v_rsq_f32_e32 v81, v81
	s_nop 0
	v_mul_f32_e32 v80, 0x45800000, v81
	v_cndmask_b32_e32 v82, v81, v80, vcc
	v_mul_f32_e32 v84, v104, v82
	v_mul_f32_e32 v85, v105, v82
	v_mul_f32_e32 v86, v106, v82
	v_mul_f32_e32 v87, v107, v82
	v_mul_f32_e32 v84, v182, v84
	v_mul_f32_e32 v85, v183, v85
	v_mul_f32_e32 v86, v184, v86
	v_mul_f32_e32 v87, v185, v87
	v_fma_f32 v84, v214, v84, v0
	v_fma_f32 v85, v215, v85, v1
	v_fma_f32 v86, v216, v86, v2
	v_fma_f32 v87, v217, v87, v3
	v_bfe_u32 v88, v84, 16, 1
	v_bfe_u32 v89, v85, 16, 1
	v_bfe_u32 v144, v86, 16, 1
	v_bfe_u32 v145, v87, 16, 1
	v_add3_u32 v84, v84, v88, s3
	v_add3_u32 v85, v85, v89, s3
	v_add3_u32 v86, v86, v144, s3
	v_add3_u32 v87, v87, v145, s3
	v_perm_b32 v146, v85, v84, s101
	v_perm_b32 v147, v87, v86, s101
	global_store_dwordx2 v[78:79], v[146:147], off
	v_mul_f32_e32 v84, v108, v82
	v_mul_f32_e32 v85, v109, v82
	v_mul_f32_e32 v86, v110, v82
	v_mul_f32_e32 v87, v111, v82
	v_mul_f32_e32 v84, v186, v84
	v_mul_f32_e32 v85, v187, v85
	v_mul_f32_e32 v86, v188, v86
	v_mul_f32_e32 v87, v189, v87
	v_fma_f32 v84, v218, v84, v4
	v_fma_f32 v85, v219, v85, v5
	v_fma_f32 v86, v220, v86, v6
	v_fma_f32 v87, v221, v87, v7
	v_bfe_u32 v88, v84, 16, 1
	v_bfe_u32 v89, v85, 16, 1
	v_bfe_u32 v144, v86, 16, 1
	v_bfe_u32 v145, v87, 16, 1
	v_add3_u32 v84, v84, v88, s3
	v_add3_u32 v85, v85, v89, s3
	v_add3_u32 v86, v86, v144, s3
	v_add3_u32 v87, v87, v145, s3
	v_perm_b32 v148, v85, v84, s101
	v_perm_b32 v149, v87, v86, s101
	global_store_dwordx2 v[78:79], v[148:149], off offset:512
	v_mul_f32_e32 v84, v112, v82
	v_mul_f32_e32 v85, v113, v82
	v_mul_f32_e32 v86, v114, v82
	v_mul_f32_e32 v87, v115, v82
	v_mul_f32_e32 v84, v190, v84
	v_mul_f32_e32 v85, v191, v85
	v_mul_f32_e32 v86, v192, v86
	v_mul_f32_e32 v87, v193, v87
	v_fma_f32 v84, v222, v84, v8
	v_fma_f32 v85, v223, v85, v9
	v_fma_f32 v86, v224, v86, v10
	v_fma_f32 v87, v225, v87, v11
	v_bfe_u32 v88, v84, 16, 1
	v_bfe_u32 v89, v85, 16, 1
	v_bfe_u32 v144, v86, 16, 1
	v_bfe_u32 v145, v87, 16, 1
	v_add3_u32 v84, v84, v88, s3
	v_add3_u32 v85, v85, v89, s3
	v_add3_u32 v86, v86, v144, s3
	v_add3_u32 v87, v87, v145, s3
	v_perm_b32 v146, v85, v84, s101
	v_perm_b32 v147, v87, v86, s101
	global_store_dwordx2 v[78:79], v[146:147], off offset:1024
	v_mul_f32_e32 v84, v116, v82
	v_mul_f32_e32 v85, v117, v82
	v_mul_f32_e32 v86, v118, v82
	v_mul_f32_e32 v87, v119, v82
	v_mul_f32_e32 v84, v194, v84
	v_mul_f32_e32 v85, v195, v85
	v_mul_f32_e32 v86, v196, v86
	v_mul_f32_e32 v87, v197, v87
	v_fma_f32 v84, v226, v84, v12
	v_fma_f32 v85, v227, v85, v13
	v_fma_f32 v86, v228, v86, v14
	v_fma_f32 v87, v229, v87, v15
	v_bfe_u32 v88, v84, 16, 1
	v_bfe_u32 v89, v85, 16, 1
	v_bfe_u32 v144, v86, 16, 1
	v_bfe_u32 v145, v87, 16, 1
	v_add3_u32 v84, v84, v88, s3
	v_add3_u32 v85, v85, v89, s3
	v_add3_u32 v86, v86, v144, s3
	v_add3_u32 v87, v87, v145, s3
	v_perm_b32 v148, v85, v84, s101
	v_perm_b32 v149, v87, v86, s101
	global_store_dwordx2 v[78:79], v[148:149], off offset:1536
	v_mul_f32_e32 v84, v120, v82
	v_mul_f32_e32 v85, v121, v82
	v_mul_f32_e32 v86, v122, v82
	v_mul_f32_e32 v87, v123, v82
	v_mul_f32_e32 v84, v198, v84
	v_mul_f32_e32 v85, v199, v85
	v_mul_f32_e32 v86, v200, v86
	v_mul_f32_e32 v87, v201, v87
	v_fma_f32 v84, v230, v84, v16
	v_fma_f32 v85, v231, v85, v17
	v_fma_f32 v86, v232, v86, v18
	v_fma_f32 v87, v233, v87, v19
	v_bfe_u32 v88, v84, 16, 1
	v_bfe_u32 v89, v85, 16, 1
	v_bfe_u32 v144, v86, 16, 1
	v_bfe_u32 v145, v87, 16, 1
	v_add3_u32 v84, v84, v88, s3
	v_add3_u32 v85, v85, v89, s3
	v_add3_u32 v86, v86, v144, s3
	v_add3_u32 v87, v87, v145, s3
	v_perm_b32 v146, v85, v84, s101
	v_perm_b32 v147, v87, v86, s101
	global_store_dwordx2 v[78:79], v[146:147], off offset:2048
	v_mul_f32_e32 v84, v124, v82
	v_mul_f32_e32 v85, v125, v82
	v_mul_f32_e32 v86, v126, v82
	v_mul_f32_e32 v87, v127, v82
	v_mul_f32_e32 v84, v202, v84
	v_mul_f32_e32 v85, v203, v85
	v_mul_f32_e32 v86, v204, v86
	v_mul_f32_e32 v87, v205, v87
	v_fma_f32 v84, v234, v84, v20
	v_fma_f32 v85, v235, v85, v21
	v_fma_f32 v86, v236, v86, v22
	v_fma_f32 v87, v237, v87, v23
	v_bfe_u32 v88, v84, 16, 1
	v_bfe_u32 v89, v85, 16, 1
	v_bfe_u32 v144, v86, 16, 1
	v_bfe_u32 v145, v87, 16, 1
	v_add3_u32 v84, v84, v88, s3
	v_add3_u32 v85, v85, v89, s3
	v_add3_u32 v86, v86, v144, s3
	v_add3_u32 v87, v87, v145, s3
	v_perm_b32 v148, v85, v84, s101
	v_perm_b32 v149, v87, v86, s101
	global_store_dwordx2 v[78:79], v[148:149], off offset:2560
	v_mul_f32_e32 v84, v128, v82
	v_mul_f32_e32 v85, v129, v82
	v_mul_f32_e32 v86, v130, v82
	v_mul_f32_e32 v87, v131, v82
	v_mul_f32_e32 v84, v206, v84
	v_mul_f32_e32 v85, v207, v85
	v_mul_f32_e32 v86, v208, v86
	v_mul_f32_e32 v87, v209, v87
	v_fma_f32 v84, v238, v84, v136
	v_fma_f32 v85, v239, v85, v137
	v_fma_f32 v86, v240, v86, v138
	v_fma_f32 v87, v241, v87, v139
	v_bfe_u32 v88, v84, 16, 1
	v_bfe_u32 v89, v85, 16, 1
	v_bfe_u32 v144, v86, 16, 1
	v_bfe_u32 v145, v87, 16, 1
	v_add3_u32 v84, v84, v88, s3
	v_add3_u32 v85, v85, v89, s3
	v_add3_u32 v86, v86, v144, s3
	v_add3_u32 v87, v87, v145, s3
	v_perm_b32 v146, v85, v84, s101
	v_perm_b32 v147, v87, v86, s101
	global_store_dwordx2 v[78:79], v[146:147], off offset:3072
	v_mul_f32_e32 v84, v132, v82
	v_mul_f32_e32 v85, v133, v82
	v_mul_f32_e32 v86, v134, v82
	v_mul_f32_e32 v87, v135, v82
	v_mul_f32_e32 v84, v210, v84
	v_mul_f32_e32 v85, v211, v85
	v_mul_f32_e32 v86, v212, v86
	v_mul_f32_e32 v87, v213, v87
	v_fma_f32 v84, v242, v84, v140
	v_fma_f32 v85, v243, v85, v141
	v_fma_f32 v86, v244, v86, v142
	v_fma_f32 v87, v245, v87, v143
	v_bfe_u32 v88, v84, 16, 1
	v_bfe_u32 v89, v85, 16, 1
	v_bfe_u32 v144, v86, 16, 1
	v_bfe_u32 v145, v87, 16, 1
	v_add3_u32 v84, v84, v88, s3
	v_add3_u32 v85, v85, v89, s3
	v_add3_u32 v86, v86, v144, s3
	v_add3_u32 v87, v87, v145, s3
	v_perm_b32 v148, v85, v84, s101
	v_perm_b32 v149, v87, v86, s101
	global_store_dwordx2 v[78:79], v[148:149], off offset:3584
